# F13 + grid barrier poll loops without s_sleep (release seen one sleep quantum earlier)
# speedup vs baseline: 1.0008x; 1.0008x over previous
.LBB1_183:
	s_and_b32 s6, s5, 0xff
	s_mov_b64 s[36:37], -1
	s_cmp_lg_u32 s6, 0
	s_mov_b64 s[40:41], -1
	s_cbranch_scc0 .LBB1_186
	s_and_b64 vcc, exec, s[40:41]
	s_cbranch_vccz .LBB1_182

.LBB1_316:
	s_and_b32 s6, s5, 0xff
	s_mov_b64 s[38:39], -1
	s_cmp_lg_u32 s6, 0
	s_mov_b64 s[42:43], -1
	s_cbranch_scc0 .LBB1_319
	s_and_b64 vcc, exec, s[42:43]
	s_cbranch_vccz .LBB1_315

.LBB1_1289:
	s_and_b32 s5, s1, 0xff
	s_mov_b64 s[36:37], -1
	s_cmp_lg_u32 s5, 0
	s_mov_b64 s[40:41], -1
	s_cbranch_scc0 .LBB1_1292
	s_and_b64 vcc, exec, s[40:41]
	s_cbranch_vccz .LBB1_1288
